# thin kv tile: waves whose B-operand LDS rows (32..63, clamped duplicates) are never read skip that LDS-DMA load; stage waits vmcnt(4)
# baseline (speedup 1.0000x reference)
; template <bool SWAP, class Epi, bool THIN = false> ...
;     ...
;     unsigned ap[4], bp[4];
; #pragma unroll
;     for (int i = 0; i < 4; ++i) {
;       const int r = (tid >> 3) + 64 * i;
;       const int cs = tid & 7;
;       const int c = ((cs ^ ((r >> 1) & 7)) << 3);
;       const int sub = 2 * mt + (r >> 7);
;       const int g = sub / tpg, ti = sub - g * tpg;
;       int rig = ti * step - halo + (r & 127); rig = rig < 0 ? 0 : (rig > grows - 1 ? grows - 1 : rig);
;       ap[i] = (unsigned)((g * a_gstride + a_goff + rig) * lda + c);
;       int br = nt * 256 + r; br = br > N - 1 ? N - 1 : br;
;       bp[i] = (unsigned)(br * K + c);
;     }
;     const bool have_next = false;
;     f32x4 acc[4][8];
; #pragma unroll
;     for (int m = 0; m < 4; ++m)
; #pragma unroll
;       for (int n = 0; n < 8; ++n) acc[m][n] = (f32x4){0.f, 0.f, 0.f, 0.f};
;     if (!pre_issued) {
; #pragma unroll
;       for (int i = 0; i < 4; ++i) { GLDS16(A + (size_t)ap[i], smem + tid * 16 + i * 8192); GLDS16(Bt + (size_t)bp[i], smem + 32768 + tid * 16 + i * 8192); }
;     }
;     pre_issued = have_next;
;     for (int st = 0; st < ns; ++st) {
;       asm volatile("s_waitcnt vmcnt(0)" ::: "memory");
;       __builtin_amdgcn_s_barrier();
;       asm volatile("" ::: "memory");
;       if (st + 1 < ns) {
;         char* nb = smem + ((st + 1) & 1) * 65536;
;         const int ko = (st + 1) * 64;
; #pragma unroll
;         for (int i = 0; i < 4; ++i) { GLDS16(A + (size_t)(ap[i] + ko), nb + tid * 16 + i * 8192); GLDS16(Bt + (size_t)(bp[i] + ko), nb + 32768 + tid * 16 + i * 8192); }
;       }
;       const char* sa = smem + (st & 1) * 65536 + (wr * 64 + fr) * 128;
;       const char* sb = smem + (st & 1) * 65536 + 32768 + (wc * 128 + fr) * 128;
;       if constexpr (THIN) {
;         if (wc == 0) {
; #pragma unroll
;           for (int ks = 0; ks < 2; ++ks) {
;             bf16x8 af[4], bf[2];
; #pragma unroll
;             for (int m = 0; m < 4; ++m) af[m] = *(const bf16x8*)(sa + m * 2048 + (((ks * 4 + fq) ^ swz) << 4));
; #pragma unroll
;             for (int n = 0; n < 2; ++n) bf[n] = *(const bf16x8*)(sb + n * 2048 + (((ks * 4 + fq) ^ swz) << 4));
; #pragma unroll
;             for (int m = 0; m < 4; ++m)
; #pragma unroll
;               for (int n = 0; n < 2; ++n)
;                 acc[m][n] = SWAP ? __builtin_amdgcn_mfma_f32_16x16x32_bf16(bf[n], af[m], acc[m][n], 0, 0, 0)
.LBB0_1525:
	s_ashr_i32 s7, s3, 31
	s_lshr_b32 s7, s7, 29
	s_add_i32 s6, s3, 0x108
	s_add_i32 s7, s3, s7
	s_and_b32 s7, s7, -8
	s_and_b32 s6, s6, 7
	s_or_b32 s6, s7, s6
	s_lshl_b32 s9, s6, 1
	v_add_u32_e32 v2, s9, v57
	v_mul_hi_i32 v4, v2, s33
	v_lshrrev_b32_e32 v5, 31, v4
	v_ashrrev_i32_e32 v4, 2, v4
	v_add_u32_e32 v6, v4, v5
	s_sub_i32 s8, s3, s7
	v_mad_u64_u32 v[4:5], s[6:7], v6, s74, v[2:3]
	v_lshl_or_b32 v2, v4, 7, v58
	v_min_i32_e32 v2, 0x8ff, v2
	v_cmp_lt_i32_e32 vcc, -1, v4
	s_ashr_i32 s46, s8, 3
	s_lshl_b32 s8, s46, 8
	v_cndmask_b32_e32 v2, 0, v2, vcc
	v_mad_u64_u32 v[4:5], s[6:7], v6, s75, v[2:3]
	v_lshl_or_b32 v2, v4, 10, v55
	v_add_u32_e32 v4, s8, v54
	v_min_i32_e32 v4, 31, v4
	v_lshl_or_b32 v38, v4, 10, v55
	v_add_u32_e32 v4, s9, v60
	v_mul_hi_i32 v5, v4, s33
	v_lshrrev_b32_e32 v6, 31, v5
	v_ashrrev_i32_e32 v5, 2, v5
	v_add_u32_e32 v6, v5, v6
	v_mad_u64_u32 v[4:5], s[6:7], v6, s74, v[4:5]
	v_lshl_or_b32 v5, v4, 7, v61
	v_min_i32_e32 v5, 0x8ff, v5
	v_cmp_lt_i32_e32 vcc, -1, v4
	v_add_u32_e32 v8, s9, v65
	v_lshl_add_u64 v[46:47], v[2:3], 1, s[36:37]
	v_cndmask_b32_e32 v4, 0, v5, vcc
	v_mad_u64_u32 v[4:5], s[6:7], v6, s75, v[4:5]
	v_add_u32_e32 v5, s8, v59
	v_min_i32_e32 v5, 31, v5
	v_add_u32_e32 v6, s9, v63
	v_lshl_or_b32 v40, v5, 10, v55
	v_mul_hi_i32 v5, v6, s33
	v_lshrrev_b32_e32 v7, 31, v5
	v_ashrrev_i32_e32 v5, 2, v5
	v_add_u32_e32 v5, v5, v7
	v_mad_u64_u32 v[6:7], s[6:7], v5, s74, v[6:7]
	v_lshl_or_b32 v7, v6, 7, v58
	v_min_i32_e32 v7, 0x8ff, v7
	v_cmp_lt_i32_e32 vcc, -1, v6
	v_mov_b32_e32 v39, v3
	v_lshl_or_b32 v4, v4, 10, v55
	v_cndmask_b32_e32 v6, 0, v7, vcc
	v_mad_u64_u32 v[6:7], s[6:7], v5, s75, v[6:7]
	v_add_u32_e32 v5, s8, v62
	v_min_i32_e32 v5, 31, v5
	v_lshl_or_b32 v42, v5, 10, v55
	v_mul_hi_i32 v5, v8, s33
	v_lshrrev_b32_e32 v7, 31, v5
	v_ashrrev_i32_e32 v5, 2, v5
	v_add_u32_e32 v5, v5, v7
	v_mad_u64_u32 v[8:9], s[6:7], v5, s74, v[8:9]
	v_lshl_or_b32 v7, v8, 7, v66
	v_min_i32_e32 v7, 0x8ff, v7
	v_cmp_lt_i32_e32 vcc, -1, v8
	v_lshl_add_u64 v[10:11], v[38:39], 1, s[18:19]
	v_mov_b32_e32 v41, v3
	v_cndmask_b32_e32 v8, 0, v7, vcc
	v_mad_u64_u32 v[8:9], s[6:7], v5, s75, v[8:9]
	v_add_u32_e32 v5, s8, v64
	v_readfirstlane_b32 s6, v56
	v_min_i32_e32 v5, 31, v5
	s_mov_b32 m0, s6
	v_readfirstlane_b32 s6, v67
	v_lshl_or_b32 v44, v5, 10, v55
	global_load_lds_dwordx4 v[46:47], off
	s_mov_b32 m0, s6
	v_mov_b32_e32 v5, v3
	v_readfirstlane_b32 s6, v68
	global_load_lds_dwordx4 v[10:11], off
	v_lshl_add_u64 v[48:49], v[4:5], 1, s[36:37]
	s_mov_b32 m0, s6
	v_readfirstlane_b32 s6, v69
	v_lshl_or_b32 v6, v6, 10, v55
	global_load_lds_dwordx4 v[48:49], off
	v_lshl_add_u64 v[4:5], v[40:41], 1, s[18:19]
	s_mov_b32 m0, s6
	v_mov_b32_e32 v7, v3
	v_readfirstlane_b32 s6, v70
	v_lshl_add_u64 v[50:51], v[6:7], 1, s[36:37]
	s_mov_b32 m0, s6
	v_mov_b32_e32 v43, v3
	v_readfirstlane_b32 s6, v71
	v_lshl_or_b32 v8, v8, 10, v55
	global_load_lds_dwordx4 v[50:51], off
	v_lshl_add_u64 v[4:5], v[42:43], 1, s[18:19]
	s_mov_b32 m0, s6
	v_mov_b32_e32 v9, v3
	v_readfirstlane_b32 s6, v72
	v_lshl_add_u64 v[52:53], v[8:9], 1, s[36:37]
	s_mov_b32 m0, s6
	v_mov_b32_e32 v45, v3
	v_readfirstlane_b32 s6, v73
	global_load_lds_dwordx4 v[52:53], off
	v_lshl_add_u64 v[4:5], v[44:45], 1, s[18:19]
	s_mov_b32 m0, s6
	v_readfirstlane_b32 s6, v74
	v_readfirstlane_b32 s6, v56
	s_add_i32 m0, s6, 0x10000
	v_lshl_add_u64 v[4:5], v[46:47], 0, s[22:23]
	global_load_lds_dwordx4 v[4:5], off
	s_cmp_ge_u32 s6, 0x1000
	s_cbranch_scc1 .Lthin_nb_1
	v_or_b32_e32 v2, 64, v38
	s_add_i32 m0, s6, 0x18000
	v_lshl_add_u64 v[4:5], v[2:3], 1, s[18:19]
	global_load_lds_dwordx4 v[4:5], off
.Lthin_nb_1:
	s_add_i32 m0, s6, 0x12000
	v_lshl_add_u64 v[4:5], v[48:49], 0, s[22:23]
	global_load_lds_dwordx4 v[4:5], off
	s_add_i32 m0, s6, 0x14000
	v_lshl_add_u64 v[4:5], v[50:51], 0, s[22:23]
	global_load_lds_dwordx4 v[4:5], off
	s_add_i32 m0, s6, 0x16000
	v_lshl_add_u64 v[4:5], v[52:53], 0, s[22:23]
	global_load_lds_dwordx4 v[4:5], off
	s_waitcnt vmcnt(4)
	s_barrier
	v_readfirstlane_b32 s6, v56
	s_add_i32 m0, s6, 0x1a000
	v_lshl_add_u64 v[4:5], v[46:47], 0, s[24:25]
	global_load_lds_dwordx4 v[4:5], off
	s_cmp_ge_u32 s6, 0x1000
	s_cbranch_scc1 .Lthin_nb_2
	v_or_b32_e32 v2, 0x80, v38
	s_add_i32 m0, s6, 0x22000
	v_lshl_add_u64 v[4:5], v[2:3], 1, s[18:19]
	global_load_lds_dwordx4 v[4:5], off
.Lthin_nb_2:
	s_add_i32 m0, s6, 0x1c000
	v_lshl_add_u64 v[4:5], v[48:49], 0, s[24:25]
	global_load_lds_dwordx4 v[4:5], off
	s_add_i32 m0, s6, 0x1e000
	v_lshl_add_u64 v[4:5], v[50:51], 0, s[24:25]
	global_load_lds_dwordx4 v[4:5], off
	s_add_i32 m0, s6, 0x20000
	v_lshl_add_u64 v[4:5], v[52:53], 0, s[24:25]
	global_load_lds_dwordx4 v[4:5], off
	v_mov_b32_e32 v2, v3
	v_mov_b32_e32 v4, v3
	v_mov_b32_e32 v5, v3
	v_mov_b64_e32 v[28:29], v[4:5]
	v_mov_b64_e32 v[24:25], v[4:5]
	v_mov_b64_e32 v[20:21], v[4:5]
	v_mov_b64_e32 v[16:17], v[4:5]
	v_mov_b64_e32 v[12:13], v[4:5]
	v_mov_b64_e32 v[8:9], v[4:5]
	v_mov_b64_e32 v[32:33], v[4:5]
	v_mov_b64_e32 v[36:37], v[4:5]
	v_mov_b64_e32 v[26:27], v[2:3]
	v_mov_b64_e32 v[22:23], v[2:3]
	v_mov_b64_e32 v[18:19], v[2:3]
	v_mov_b64_e32 v[14:15], v[2:3]
	v_mov_b64_e32 v[10:11], v[2:3]
	v_mov_b64_e32 v[6:7], v[2:3]
	v_mov_b64_e32 v[30:31], v[2:3]
	v_mov_b64_e32 v[34:35], v[2:3]
	s_and_saveexec_b64 s[6:7], s[4:5]
	s_cbranch_execz .LBB0_1527
	ds_read_b128 v[4:7], v83 offset:32768
	ds_read_b128 v[8:11], v83 offset:34816
	ds_read_b128 v[12:15], v82
	ds_read_b128 v[16:19], v82 offset:2048
	ds_read_b128 v[28:31], v82 offset:4096
	ds_read_b128 v[32:35], v82 offset:6144
	ds_read_b128 v[102:105], v85 offset:32768
	s_waitcnt lgkmcnt(0)
	v_mfma_f32_16x16x32_bf16 v[20:23], v[4:7], v[12:15], 0
	v_mfma_f32_16x16x32_bf16 v[12:15], v[8:11], v[12:15], 0
	v_mfma_f32_16x16x32_bf16 v[24:27], v[4:7], v[16:19], 0
	v_mfma_f32_16x16x32_bf16 v[16:19], v[8:11], v[16:19], 0
	v_mfma_f32_16x16x32_bf16 v[98:101], v[8:11], v[28:31], 0
	v_mfma_f32_16x16x32_bf16 v[106:109], v[8:11], v[32:35], 0
	ds_read_b128 v[110:113], v85 offset:34816
	ds_read_b128 v[8:11], v84
	ds_read_b128 v[114:117], v84 offset:2048
	v_mfma_f32_16x16x32_bf16 v[94:97], v[4:7], v[28:31], 0
	v_mfma_f32_16x16x32_bf16 v[4:7], v[4:7], v[32:35], 0
	s_waitcnt lgkmcnt(0)
	v_mfma_f32_16x16x32_bf16 v[34:37], v[102:105], v[8:11], v[20:23]
	v_mfma_f32_16x16x32_bf16 v[30:33], v[110:113], v[8:11], v[12:15]
	v_mfma_f32_16x16x32_bf16 v[26:29], v[102:105], v[114:117], v[24:27]
	v_mfma_f32_16x16x32_bf16 v[22:25], v[110:113], v[114:117], v[16:19]
	ds_read_b128 v[8:11], v84 offset:4096
	ds_read_b128 v[114:117], v84 offset:6144
	s_waitcnt lgkmcnt(0)
	v_mfma_f32_16x16x32_bf16 v[18:21], v[102:105], v[8:11], v[94:97]
	v_mfma_f32_16x16x32_bf16 v[14:17], v[110:113], v[8:11], v[98:101]
	v_mfma_f32_16x16x32_bf16 v[10:13], v[102:105], v[114:117], v[4:7]
	v_mfma_f32_16x16x32_bf16 v[6:9], v[110:113], v[114:117], v[106:109]
; #define GLDS16(gp, lp) __builtin_amdgcn_global_load_lds((const unsigned*)(gp), (__attribute__((address_space(3))) unsigned*)(lp), 16, 0, 0)
; template <bool SWAP, class Epi, bool THIN = false> ...
;     ...
;     for (int st = 0; st < ns; ++st) {
;       asm volatile("s_waitcnt vmcnt(0)" ::: "memory");
;       __builtin_amdgcn_s_barrier();
;       asm volatile("" ::: "memory");
;       if (st + 1 < ns) {
;         char* nb = smem + ((st + 1) & 1) * 65536;
;         const int ko = (st + 1) * 64;
; #pragma unroll
;         for (int i = 0; i < 4; ++i) { GLDS16(A + (size_t)(ap[i] + ko), nb + tid * 16 + i * 8192); GLDS16(Bt + (size_t)(bp[i] + ko), nb + 32768 + tid * 16 + i * 8192); }
;       }
;       const char* sa = smem + (st & 1) * 65536 + (wr * 64 + fr) * 128;
;       const char* sb = smem + (st & 1) * 65536 + 32768 + (wc * 128 + fr) * 128;
;       if constexpr (THIN) {
;         if (wc == 0) {
; #pragma unroll
;           for (int ks = 0; ks < 2; ++ks) {
;             bf16x8 af[4], bf[2];
; #pragma unroll
;             for (int m = 0; m < 4; ++m) af[m] = *(const bf16x8*)(sa + m * 2048 + (((ks * 4 + fq) ^ swz) << 4));
; #pragma unroll
;             for (int n = 0; n < 2; ++n) bf[n] = *(const bf16x8*)(sb + n * 2048 + (((ks * 4 + fq) ^ swz) << 4));
; #pragma unroll
;             for (int m = 0; m < 4; ++m)
; #pragma unroll
;               for (int n = 0; n < 2; ++n)
;                 acc[m][n] = SWAP ? __builtin_amdgcn_mfma_f32_16x16x32_bf16(bf[n], af[m], acc[m][n], 0, 0, 0)
;                                  : __builtin_amdgcn_mfma_f32_16x16x32_bf16(af[m], bf[n], acc[m][n], 0, 0, 0);
;           }
;         }
.LBB0_1527:
	s_or_b64 exec, exec, s[6:7]
	s_waitcnt vmcnt(4)
	s_barrier
	v_readfirstlane_b32 s6, v56
	s_add_i32 m0, s6, 0x0
	v_lshl_add_u64 v[4:5], v[46:47], 0, s[26:27]
	global_load_lds_dwordx4 v[4:5], off
	s_cmp_ge_u32 s6, 0x1000
	s_cbranch_scc1 .Lthin_nb_3
	v_or_b32_e32 v2, 0xc0, v38
	s_add_i32 m0, s6, 0x8000
	v_lshl_add_u64 v[4:5], v[2:3], 1, s[18:19]
	global_load_lds_dwordx4 v[4:5], off
.Lthin_nb_3:
	s_add_i32 m0, s6, 0x2000
	v_lshl_add_u64 v[4:5], v[48:49], 0, s[26:27]
	global_load_lds_dwordx4 v[4:5], off
	s_add_i32 m0, s6, 0x4000
	v_lshl_add_u64 v[4:5], v[50:51], 0, s[26:27]
	global_load_lds_dwordx4 v[4:5], off
	s_add_i32 m0, s6, 0x6000
	v_lshl_add_u64 v[4:5], v[52:53], 0, s[26:27]
	global_load_lds_dwordx4 v[4:5], off
	s_and_saveexec_b64 s[6:7], s[4:5]
	s_cbranch_execz .LBB0_1529
	ds_read_b128 v[94:97], v87
	ds_read_b128 v[98:101], v87 offset:2048
	ds_read_b128 v[102:105], v86
	ds_read_b128 v[106:109], v86 offset:2048
	s_waitcnt lgkmcnt(0)
	v_mfma_f32_16x16x32_bf16 v[34:37], v[94:97], v[102:105], v[34:37]
	v_mfma_f32_16x16x32_bf16 v[30:33], v[98:101], v[102:105], v[30:33]
	v_mfma_f32_16x16x32_bf16 v[26:29], v[94:97], v[106:109], v[26:29]
	v_mfma_f32_16x16x32_bf16 v[22:25], v[98:101], v[106:109], v[22:25]
	ds_read_b128 v[102:105], v86 offset:4096
	ds_read_b128 v[106:109], v86 offset:6144
	s_waitcnt lgkmcnt(0)
	v_mfma_f32_16x16x32_bf16 v[18:21], v[94:97], v[102:105], v[18:21]
	v_mfma_f32_16x16x32_bf16 v[10:13], v[94:97], v[106:109], v[10:13]
	ds_read_b128 v[94:97], v89
	v_mfma_f32_16x16x32_bf16 v[14:17], v[98:101], v[102:105], v[14:17]
	v_mfma_f32_16x16x32_bf16 v[4:7], v[98:101], v[106:109], v[6:9]
	ds_read_b128 v[98:101], v89 offset:2048
	ds_read_b128 v[102:105], v88
	ds_read_b128 v[106:109], v88 offset:2048
	s_waitcnt lgkmcnt(0)
	v_mfma_f32_16x16x32_bf16 v[34:37], v[94:97], v[102:105], v[34:37]
	v_mfma_f32_16x16x32_bf16 v[30:33], v[98:101], v[102:105], v[30:33]
	v_mfma_f32_16x16x32_bf16 v[26:29], v[94:97], v[106:109], v[26:29]
	v_mfma_f32_16x16x32_bf16 v[22:25], v[98:101], v[106:109], v[22:25]
	ds_read_b128 v[102:105], v88 offset:4096
	ds_read_b128 v[106:109], v88 offset:6144
	s_waitcnt lgkmcnt(0)
	v_mfma_f32_16x16x32_bf16 v[18:21], v[94:97], v[102:105], v[18:21]
	v_mfma_f32_16x16x32_bf16 v[14:17], v[98:101], v[102:105], v[14:17]
	v_mfma_f32_16x16x32_bf16 v[10:13], v[94:97], v[106:109], v[10:13]
	v_mfma_f32_16x16x32_bf16 v[6:9], v[98:101], v[106:109], v[4:7]
.LBB0_1529:
	s_or_b64 exec, exec, s[6:7]
	s_waitcnt vmcnt(4)
	s_barrier
	v_readfirstlane_b32 s6, v56
	s_add_i32 m0, s6, 0x10000
	v_lshl_add_u64 v[4:5], v[46:47], 0, s[28:29]
	global_load_lds_dwordx4 v[4:5], off
	s_cmp_ge_u32 s6, 0x1000
	s_cbranch_scc1 .Lthin_nb_4
	v_or_b32_e32 v2, 0x100, v38
	s_add_i32 m0, s6, 0x18000
	v_lshl_add_u64 v[4:5], v[2:3], 1, s[18:19]
	global_load_lds_dwordx4 v[4:5], off
.Lthin_nb_4:
	s_add_i32 m0, s6, 0x12000
	v_lshl_add_u64 v[4:5], v[48:49], 0, s[28:29]
	global_load_lds_dwordx4 v[4:5], off
	s_add_i32 m0, s6, 0x14000
	v_lshl_add_u64 v[4:5], v[50:51], 0, s[28:29]
	global_load_lds_dwordx4 v[4:5], off
	s_add_i32 m0, s6, 0x16000
	v_lshl_add_u64 v[4:5], v[52:53], 0, s[28:29]
	global_load_lds_dwordx4 v[4:5], off
	s_and_saveexec_b64 s[6:7], s[4:5]
	s_cbranch_execz .LBB0_1531
	ds_read_b128 v[94:97], v119 offset:32768
	ds_read_b128 v[98:101], v119 offset:34816
	ds_read_b128 v[102:105], v118
	ds_read_b128 v[106:109], v118 offset:2048
	s_waitcnt lgkmcnt(0)
	v_mfma_f32_16x16x32_bf16 v[34:37], v[94:97], v[102:105], v[34:37]
	v_mfma_f32_16x16x32_bf16 v[30:33], v[98:101], v[102:105], v[30:33]
	v_mfma_f32_16x16x32_bf16 v[26:29], v[94:97], v[106:109], v[26:29]
	v_mfma_f32_16x16x32_bf16 v[22:25], v[98:101], v[106:109], v[22:25]
	ds_read_b128 v[102:105], v118 offset:4096
	ds_read_b128 v[106:109], v118 offset:6144
	s_waitcnt lgkmcnt(0)
	v_mfma_f32_16x16x32_bf16 v[18:21], v[94:97], v[102:105], v[18:21]
	v_mfma_f32_16x16x32_bf16 v[10:13], v[94:97], v[106:109], v[10:13]
	ds_read_b128 v[94:97], v121 offset:32768
	v_mfma_f32_16x16x32_bf16 v[14:17], v[98:101], v[102:105], v[14:17]
	v_mfma_f32_16x16x32_bf16 v[4:7], v[98:101], v[106:109], v[6:9]
	ds_read_b128 v[98:101], v121 offset:34816
	ds_read_b128 v[102:105], v120
	ds_read_b128 v[106:109], v120 offset:2048
	s_waitcnt lgkmcnt(0)
	v_mfma_f32_16x16x32_bf16 v[34:37], v[94:97], v[102:105], v[34:37]
	v_mfma_f32_16x16x32_bf16 v[30:33], v[98:101], v[102:105], v[30:33]
	v_mfma_f32_16x16x32_bf16 v[26:29], v[94:97], v[106:109], v[26:29]
	v_mfma_f32_16x16x32_bf16 v[22:25], v[98:101], v[106:109], v[22:25]
	ds_read_b128 v[102:105], v120 offset:4096
	ds_read_b128 v[106:109], v120 offset:6144
	s_waitcnt lgkmcnt(0)
	v_mfma_f32_16x16x32_bf16 v[18:21], v[94:97], v[102:105], v[18:21]
	v_mfma_f32_16x16x32_bf16 v[14:17], v[98:101], v[102:105], v[14:17]
	v_mfma_f32_16x16x32_bf16 v[10:13], v[94:97], v[106:109], v[10:13]
	v_mfma_f32_16x16x32_bf16 v[6:9], v[98:101], v[106:109], v[4:7]
.LBB0_1531:
	s_or_b64 exec, exec, s[6:7]
	s_waitcnt vmcnt(4)
	s_barrier
	v_readfirstlane_b32 s6, v56
	s_add_i32 m0, s6, 0x1a000
	v_lshl_add_u64 v[4:5], v[46:47], 0, s[38:39]
	global_load_lds_dwordx4 v[4:5], off
	s_cmp_ge_u32 s6, 0x1000
	s_cbranch_scc1 .Lthin_nb_5
	v_or_b32_e32 v2, 0x140, v38
	s_add_i32 m0, s6, 0x22000
	v_lshl_add_u64 v[4:5], v[2:3], 1, s[18:19]
	global_load_lds_dwordx4 v[4:5], off
; #define GLDS16(gp, lp) __builtin_amdgcn_global_load_lds((const unsigned*)(gp), (__attribute__((address_space(3))) unsigned*)(lp), 16, 0, 0)
; template <bool SWAP, class Epi, bool THIN = false> ...
;     ...
;     for (int st = 0; st < ns; ++st) {
;       asm volatile("s_waitcnt vmcnt(0)" ::: "memory");
;       __builtin_amdgcn_s_barrier();
;       asm volatile("" ::: "memory");
;       if (st + 1 < ns) {
;         char* nb = smem + ((st + 1) & 1) * 65536;
;         const int ko = (st + 1) * 64;
; #pragma unroll
;         for (int i = 0; i < 4; ++i) { GLDS16(A + (size_t)(ap[i] + ko), nb + tid * 16 + i * 8192); GLDS16(Bt + (size_t)(bp[i] + ko), nb + 32768 + tid * 16 + i * 8192); }
;       }
;       const char* sa = smem + (st & 1) * 65536 + (wr * 64 + fr) * 128;
;       const char* sb = smem + (st & 1) * 65536 + 32768 + (wc * 128 + fr) * 128;
;       if constexpr (THIN) {
;         if (wc == 0) {
; #pragma unroll
;           for (int ks = 0; ks < 2; ++ks) {
;             bf16x8 af[4], bf[2];
; #pragma unroll
;             for (int m = 0; m < 4; ++m) af[m] = *(const bf16x8*)(sa + m * 2048 + (((ks * 4 + fq) ^ swz) << 4));
; #pragma unroll
;             for (int n = 0; n < 2; ++n) bf[n] = *(const bf16x8*)(sb + n * 2048 + (((ks * 4 + fq) ^ swz) << 4));
; #pragma unroll
;             for (int m = 0; m < 4; ++m)
; #pragma unroll
;               for (int n = 0; n < 2; ++n)
;                 acc[m][n] = SWAP ? __builtin_amdgcn_mfma_f32_16x16x32_bf16(bf[n], af[m], acc[m][n], 0, 0, 0)
;                                  : __builtin_amdgcn_mfma_f32_16x16x32_bf16(af[m], bf[n], acc[m][n], 0, 0, 0);
;           }
;         }
.Lthin_nb_5:
	s_add_i32 m0, s6, 0x1c000
	v_lshl_add_u64 v[4:5], v[48:49], 0, s[38:39]
	global_load_lds_dwordx4 v[4:5], off
	s_add_i32 m0, s6, 0x1e000
	v_lshl_add_u64 v[4:5], v[50:51], 0, s[38:39]
	global_load_lds_dwordx4 v[4:5], off
	s_add_i32 m0, s6, 0x20000
	v_lshl_add_u64 v[4:5], v[52:53], 0, s[38:39]
	global_load_lds_dwordx4 v[4:5], off
	s_and_saveexec_b64 s[6:7], s[4:5]
	s_cbranch_execz .LBB0_1533
	ds_read_b128 v[94:97], v83 offset:32768
	ds_read_b128 v[98:101], v83 offset:34816
	ds_read_b128 v[102:105], v82
	ds_read_b128 v[106:109], v82 offset:2048
	s_waitcnt lgkmcnt(0)
	v_mfma_f32_16x16x32_bf16 v[34:37], v[94:97], v[102:105], v[34:37]
	v_mfma_f32_16x16x32_bf16 v[30:33], v[98:101], v[102:105], v[30:33]
	v_mfma_f32_16x16x32_bf16 v[26:29], v[94:97], v[106:109], v[26:29]
	v_mfma_f32_16x16x32_bf16 v[22:25], v[98:101], v[106:109], v[22:25]
	ds_read_b128 v[102:105], v82 offset:4096
	ds_read_b128 v[106:109], v82 offset:6144
	s_waitcnt lgkmcnt(0)
	v_mfma_f32_16x16x32_bf16 v[18:21], v[94:97], v[102:105], v[18:21]
	v_mfma_f32_16x16x32_bf16 v[10:13], v[94:97], v[106:109], v[10:13]
	ds_read_b128 v[94:97], v85 offset:32768
	v_mfma_f32_16x16x32_bf16 v[14:17], v[98:101], v[102:105], v[14:17]
	v_mfma_f32_16x16x32_bf16 v[4:7], v[98:101], v[106:109], v[6:9]
	ds_read_b128 v[98:101], v85 offset:34816
	ds_read_b128 v[102:105], v84
	ds_read_b128 v[106:109], v84 offset:2048
	s_waitcnt lgkmcnt(0)
	v_mfma_f32_16x16x32_bf16 v[34:37], v[94:97], v[102:105], v[34:37]
	v_mfma_f32_16x16x32_bf16 v[30:33], v[98:101], v[102:105], v[30:33]
	v_mfma_f32_16x16x32_bf16 v[26:29], v[94:97], v[106:109], v[26:29]
	v_mfma_f32_16x16x32_bf16 v[22:25], v[98:101], v[106:109], v[22:25]
	ds_read_b128 v[102:105], v84 offset:4096
	ds_read_b128 v[106:109], v84 offset:6144
	s_waitcnt lgkmcnt(0)
	v_mfma_f32_16x16x32_bf16 v[18:21], v[94:97], v[102:105], v[18:21]
	v_mfma_f32_16x16x32_bf16 v[14:17], v[98:101], v[102:105], v[14:17]
	v_mfma_f32_16x16x32_bf16 v[10:13], v[94:97], v[106:109], v[10:13]
	v_mfma_f32_16x16x32_bf16 v[6:9], v[98:101], v[106:109], v[4:7]
.LBB0_1533:
	s_or_b64 exec, exec, s[6:7]
	s_waitcnt vmcnt(4)
	s_barrier
	v_readfirstlane_b32 s6, v56
	s_add_i32 m0, s6, 0x0
	v_lshl_add_u64 v[4:5], v[46:47], 0, s[40:41]
	global_load_lds_dwordx4 v[4:5], off
	s_cmp_ge_u32 s6, 0x1000
	s_cbranch_scc1 .Lthin_nb_6
	v_or_b32_e32 v2, 0x180, v38
	s_add_i32 m0, s6, 0x8000
	v_lshl_add_u64 v[4:5], v[2:3], 1, s[18:19]
	global_load_lds_dwordx4 v[4:5], off
.Lthin_nb_6:
	s_add_i32 m0, s6, 0x2000
	v_lshl_add_u64 v[4:5], v[48:49], 0, s[40:41]
	global_load_lds_dwordx4 v[4:5], off
	s_add_i32 m0, s6, 0x4000
	v_lshl_add_u64 v[4:5], v[50:51], 0, s[40:41]
	global_load_lds_dwordx4 v[4:5], off
	s_add_i32 m0, s6, 0x6000
	v_lshl_add_u64 v[4:5], v[52:53], 0, s[40:41]
	global_load_lds_dwordx4 v[4:5], off
	s_and_saveexec_b64 s[6:7], s[4:5]
	s_cbranch_execz .LBB0_1535
	ds_read_b128 v[94:97], v87
	ds_read_b128 v[98:101], v87 offset:2048
	ds_read_b128 v[102:105], v86
	ds_read_b128 v[106:109], v86 offset:2048
	s_waitcnt lgkmcnt(0)
	v_mfma_f32_16x16x32_bf16 v[34:37], v[94:97], v[102:105], v[34:37]
	v_mfma_f32_16x16x32_bf16 v[30:33], v[98:101], v[102:105], v[30:33]
	v_mfma_f32_16x16x32_bf16 v[26:29], v[94:97], v[106:109], v[26:29]
	v_mfma_f32_16x16x32_bf16 v[22:25], v[98:101], v[106:109], v[22:25]
	ds_read_b128 v[102:105], v86 offset:4096
	ds_read_b128 v[106:109], v86 offset:6144
	s_waitcnt lgkmcnt(0)
	v_mfma_f32_16x16x32_bf16 v[18:21], v[94:97], v[102:105], v[18:21]
	v_mfma_f32_16x16x32_bf16 v[10:13], v[94:97], v[106:109], v[10:13]
	ds_read_b128 v[94:97], v89
	v_mfma_f32_16x16x32_bf16 v[14:17], v[98:101], v[102:105], v[14:17]
	v_mfma_f32_16x16x32_bf16 v[4:7], v[98:101], v[106:109], v[6:9]
	ds_read_b128 v[98:101], v89 offset:2048
	ds_read_b128 v[102:105], v88
	ds_read_b128 v[106:109], v88 offset:2048
	s_waitcnt lgkmcnt(0)
	v_mfma_f32_16x16x32_bf16 v[34:37], v[94:97], v[102:105], v[34:37]
	v_mfma_f32_16x16x32_bf16 v[30:33], v[98:101], v[102:105], v[30:33]
	v_mfma_f32_16x16x32_bf16 v[26:29], v[94:97], v[106:109], v[26:29]
	v_mfma_f32_16x16x32_bf16 v[22:25], v[98:101], v[106:109], v[22:25]
	ds_read_b128 v[102:105], v88 offset:4096
	ds_read_b128 v[106:109], v88 offset:6144
	s_waitcnt lgkmcnt(0)
	v_mfma_f32_16x16x32_bf16 v[18:21], v[94:97], v[102:105], v[18:21]
	v_mfma_f32_16x16x32_bf16 v[14:17], v[98:101], v[102:105], v[14:17]
	v_mfma_f32_16x16x32_bf16 v[10:13], v[94:97], v[106:109], v[10:13]
	v_mfma_f32_16x16x32_bf16 v[6:9], v[98:101], v[106:109], v[4:7]
.LBB0_1535:
	s_or_b64 exec, exec, s[6:7]
	s_waitcnt vmcnt(4)
	s_barrier
	v_readfirstlane_b32 s6, v56
	s_add_i32 m0, s6, 0x10000
	v_lshl_add_u64 v[4:5], v[46:47], 0, s[42:43]
	global_load_lds_dwordx4 v[4:5], off
	s_cmp_ge_u32 s6, 0x1000
	s_cbranch_scc1 .Lthin_nb_7
	v_or_b32_e32 v2, 0x1c0, v38
	s_add_i32 m0, s6, 0x18000
	v_lshl_add_u64 v[4:5], v[2:3], 1, s[18:19]
	global_load_lds_dwordx4 v[4:5], off
; #define GLDS16(gp, lp) __builtin_amdgcn_global_load_lds((const unsigned*)(gp), (__attribute__((address_space(3))) unsigned*)(lp), 16, 0, 0)
; template <bool SWAP, class Epi, bool THIN = false> ...
;     ...
;     for (int st = 0; st < ns; ++st) {
;       asm volatile("s_waitcnt vmcnt(0)" ::: "memory");
;       __builtin_amdgcn_s_barrier();
;       asm volatile("" ::: "memory");
;       if (st + 1 < ns) {
;         char* nb = smem + ((st + 1) & 1) * 65536;
;         const int ko = (st + 1) * 64;
; #pragma unroll
;         for (int i = 0; i < 4; ++i) { GLDS16(A + (size_t)(ap[i] + ko), nb + tid * 16 + i * 8192); GLDS16(Bt + (size_t)(bp[i] + ko), nb + 32768 + tid * 16 + i * 8192); }
;       }
;       const char* sa = smem + (st & 1) * 65536 + (wr * 64 + fr) * 128;
;       const char* sb = smem + (st & 1) * 65536 + 32768 + (wc * 128 + fr) * 128;
;       if constexpr (THIN) {
;         if (wc == 0) {
; #pragma unroll
;           for (int ks = 0; ks < 2; ++ks) {
;             bf16x8 af[4], bf[2];
; #pragma unroll
;             for (int m = 0; m < 4; ++m) af[m] = *(const bf16x8*)(sa + m * 2048 + (((ks * 4 + fq) ^ swz) << 4));
; #pragma unroll
;             for (int n = 0; n < 2; ++n) bf[n] = *(const bf16x8*)(sb + n * 2048 + (((ks * 4 + fq) ^ swz) << 4));
; #pragma unroll
;             for (int m = 0; m < 4; ++m)
; #pragma unroll
;               for (int n = 0; n < 2; ++n)
;                 acc[m][n] = SWAP ? __builtin_amdgcn_mfma_f32_16x16x32_bf16(bf[n], af[m], acc[m][n], 0, 0, 0)
;                                  : __builtin_amdgcn_mfma_f32_16x16x32_bf16(af[m], bf[n], acc[m][n], 0, 0, 0);
;           }
;         }
.Lthin_nb_7:
	s_add_i32 m0, s6, 0x12000
	v_lshl_add_u64 v[4:5], v[48:49], 0, s[42:43]
	global_load_lds_dwordx4 v[4:5], off
	s_add_i32 m0, s6, 0x14000
	v_lshl_add_u64 v[4:5], v[50:51], 0, s[42:43]
	global_load_lds_dwordx4 v[4:5], off
	s_add_i32 m0, s6, 0x16000
	v_lshl_add_u64 v[4:5], v[52:53], 0, s[42:43]
	global_load_lds_dwordx4 v[4:5], off
	s_and_saveexec_b64 s[6:7], s[4:5]
	s_cbranch_execz .LBB0_1537
	ds_read_b128 v[94:97], v119 offset:32768
	ds_read_b128 v[98:101], v119 offset:34816
	ds_read_b128 v[102:105], v118
	ds_read_b128 v[106:109], v118 offset:2048
	s_waitcnt lgkmcnt(0)
	v_mfma_f32_16x16x32_bf16 v[34:37], v[94:97], v[102:105], v[34:37]
	v_mfma_f32_16x16x32_bf16 v[30:33], v[98:101], v[102:105], v[30:33]
	v_mfma_f32_16x16x32_bf16 v[26:29], v[94:97], v[106:109], v[26:29]
	v_mfma_f32_16x16x32_bf16 v[22:25], v[98:101], v[106:109], v[22:25]
	ds_read_b128 v[102:105], v118 offset:4096
	ds_read_b128 v[106:109], v118 offset:6144
	s_waitcnt lgkmcnt(0)
	v_mfma_f32_16x16x32_bf16 v[18:21], v[94:97], v[102:105], v[18:21]
	v_mfma_f32_16x16x32_bf16 v[10:13], v[94:97], v[106:109], v[10:13]
	ds_read_b128 v[94:97], v121 offset:32768
	v_mfma_f32_16x16x32_bf16 v[14:17], v[98:101], v[102:105], v[14:17]
	v_mfma_f32_16x16x32_bf16 v[4:7], v[98:101], v[106:109], v[6:9]
	ds_read_b128 v[98:101], v121 offset:34816
	ds_read_b128 v[102:105], v120
	ds_read_b128 v[106:109], v120 offset:2048
	s_waitcnt lgkmcnt(0)
	v_mfma_f32_16x16x32_bf16 v[34:37], v[94:97], v[102:105], v[34:37]
	v_mfma_f32_16x16x32_bf16 v[30:33], v[98:101], v[102:105], v[30:33]
	v_mfma_f32_16x16x32_bf16 v[26:29], v[94:97], v[106:109], v[26:29]
	v_mfma_f32_16x16x32_bf16 v[22:25], v[98:101], v[106:109], v[22:25]
	ds_read_b128 v[102:105], v120 offset:4096
	ds_read_b128 v[106:109], v120 offset:6144
	s_waitcnt lgkmcnt(0)
	v_mfma_f32_16x16x32_bf16 v[18:21], v[94:97], v[102:105], v[18:21]
	v_mfma_f32_16x16x32_bf16 v[14:17], v[98:101], v[102:105], v[14:17]
	v_mfma_f32_16x16x32_bf16 v[10:13], v[94:97], v[106:109], v[10:13]
	v_mfma_f32_16x16x32_bf16 v[6:9], v[98:101], v[106:109], v[4:7]
.LBB0_1537:
	s_or_b64 exec, exec, s[6:7]
	s_waitcnt vmcnt(4)
	s_barrier
	v_readfirstlane_b32 s6, v56
	s_add_i32 m0, s6, 0x1a000
	v_lshl_add_u64 v[4:5], v[46:47], 0, s[44:45]
	global_load_lds_dwordx4 v[4:5], off
	s_cmp_ge_u32 s6, 0x1000
	s_cbranch_scc1 .Lthin_nb_8
	v_or_b32_e32 v2, 0x200, v38
	s_add_i32 m0, s6, 0x22000
	v_lshl_add_u64 v[4:5], v[2:3], 1, s[18:19]
	global_load_lds_dwordx4 v[4:5], off
.Lthin_nb_8:
	s_add_i32 m0, s6, 0x1c000
	v_lshl_add_u64 v[4:5], v[48:49], 0, s[44:45]
	global_load_lds_dwordx4 v[4:5], off
	s_add_i32 m0, s6, 0x1e000
	v_lshl_add_u64 v[4:5], v[50:51], 0, s[44:45]
	global_load_lds_dwordx4 v[4:5], off
	s_add_i32 m0, s6, 0x20000
	v_lshl_add_u64 v[4:5], v[52:53], 0, s[44:45]
	global_load_lds_dwordx4 v[4:5], off
	s_and_saveexec_b64 s[6:7], s[4:5]
	s_cbranch_execz .LBB0_1539
	ds_read_b128 v[94:97], v83 offset:32768
	ds_read_b128 v[98:101], v83 offset:34816
	ds_read_b128 v[102:105], v82
	ds_read_b128 v[106:109], v82 offset:2048
	s_waitcnt lgkmcnt(0)
	v_mfma_f32_16x16x32_bf16 v[34:37], v[94:97], v[102:105], v[34:37]
	v_mfma_f32_16x16x32_bf16 v[30:33], v[98:101], v[102:105], v[30:33]
	v_mfma_f32_16x16x32_bf16 v[26:29], v[94:97], v[106:109], v[26:29]
	v_mfma_f32_16x16x32_bf16 v[22:25], v[98:101], v[106:109], v[22:25]
	ds_read_b128 v[102:105], v82 offset:4096
	ds_read_b128 v[106:109], v82 offset:6144
	s_waitcnt lgkmcnt(0)
	v_mfma_f32_16x16x32_bf16 v[18:21], v[94:97], v[102:105], v[18:21]
	v_mfma_f32_16x16x32_bf16 v[10:13], v[94:97], v[106:109], v[10:13]
	ds_read_b128 v[94:97], v85 offset:32768
	v_mfma_f32_16x16x32_bf16 v[14:17], v[98:101], v[102:105], v[14:17]
	v_mfma_f32_16x16x32_bf16 v[4:7], v[98:101], v[106:109], v[6:9]
	ds_read_b128 v[98:101], v85 offset:34816
	ds_read_b128 v[102:105], v84
	ds_read_b128 v[106:109], v84 offset:2048
	s_waitcnt lgkmcnt(0)
	v_mfma_f32_16x16x32_bf16 v[34:37], v[94:97], v[102:105], v[34:37]
	v_mfma_f32_16x16x32_bf16 v[30:33], v[98:101], v[102:105], v[30:33]
	v_mfma_f32_16x16x32_bf16 v[26:29], v[94:97], v[106:109], v[26:29]
	v_mfma_f32_16x16x32_bf16 v[22:25], v[98:101], v[106:109], v[22:25]
	ds_read_b128 v[102:105], v84 offset:4096
	ds_read_b128 v[106:109], v84 offset:6144
	s_waitcnt lgkmcnt(0)
	v_mfma_f32_16x16x32_bf16 v[18:21], v[94:97], v[102:105], v[18:21]
	v_mfma_f32_16x16x32_bf16 v[14:17], v[98:101], v[102:105], v[14:17]
	v_mfma_f32_16x16x32_bf16 v[10:13], v[94:97], v[106:109], v[10:13]
	v_mfma_f32_16x16x32_bf16 v[6:9], v[98:101], v[106:109], v[4:7]
.LBB0_1539:
	s_or_b64 exec, exec, s[6:7]
	s_waitcnt vmcnt(4)
	s_barrier
	v_readfirstlane_b32 s6, v56
	s_add_i32 m0, s6, 0x0
	v_lshl_add_u64 v[4:5], v[46:47], 0, s[48:49]
	global_load_lds_dwordx4 v[4:5], off
	s_cmp_ge_u32 s6, 0x1000
	s_cbranch_scc1 .Lthin_nb_9
	v_or_b32_e32 v2, 0x240, v38
	s_add_i32 m0, s6, 0x8000
	v_lshl_add_u64 v[4:5], v[2:3], 1, s[18:19]
	global_load_lds_dwordx4 v[4:5], off
; #define GLDS16(gp, lp) __builtin_amdgcn_global_load_lds((const unsigned*)(gp), (__attribute__((address_space(3))) unsigned*)(lp), 16, 0, 0)
; template <bool SWAP, class Epi, bool THIN = false> ...
;     ...
;     for (int st = 0; st < ns; ++st) {
;       asm volatile("s_waitcnt vmcnt(0)" ::: "memory");
;       __builtin_amdgcn_s_barrier();
;       asm volatile("" ::: "memory");
;       if (st + 1 < ns) {
;         char* nb = smem + ((st + 1) & 1) * 65536;
;         const int ko = (st + 1) * 64;
; #pragma unroll
;         for (int i = 0; i < 4; ++i) { GLDS16(A + (size_t)(ap[i] + ko), nb + tid * 16 + i * 8192); GLDS16(Bt + (size_t)(bp[i] + ko), nb + 32768 + tid * 16 + i * 8192); }
;       }
;       const char* sa = smem + (st & 1) * 65536 + (wr * 64 + fr) * 128;
;       const char* sb = smem + (st & 1) * 65536 + 32768 + (wc * 128 + fr) * 128;
;       if constexpr (THIN) {
;         if (wc == 0) {
; #pragma unroll
;           for (int ks = 0; ks < 2; ++ks) {
;             bf16x8 af[4], bf[2];
; #pragma unroll
;             for (int m = 0; m < 4; ++m) af[m] = *(const bf16x8*)(sa + m * 2048 + (((ks * 4 + fq) ^ swz) << 4));
; #pragma unroll
;             for (int n = 0; n < 2; ++n) bf[n] = *(const bf16x8*)(sb + n * 2048 + (((ks * 4 + fq) ^ swz) << 4));
; #pragma unroll
;             for (int m = 0; m < 4; ++m)
; #pragma unroll
;               for (int n = 0; n < 2; ++n)
;                 acc[m][n] = SWAP ? __builtin_amdgcn_mfma_f32_16x16x32_bf16(bf[n], af[m], acc[m][n], 0, 0, 0)
;                                  : __builtin_amdgcn_mfma_f32_16x16x32_bf16(af[m], bf[n], acc[m][n], 0, 0, 0);
;           }
;         }
.Lthin_nb_9:
	s_add_i32 m0, s6, 0x2000
	v_lshl_add_u64 v[4:5], v[48:49], 0, s[48:49]
	global_load_lds_dwordx4 v[4:5], off
	s_add_i32 m0, s6, 0x4000
	v_lshl_add_u64 v[4:5], v[50:51], 0, s[48:49]
	global_load_lds_dwordx4 v[4:5], off
	s_add_i32 m0, s6, 0x6000
	v_lshl_add_u64 v[4:5], v[52:53], 0, s[48:49]
	global_load_lds_dwordx4 v[4:5], off
	s_and_saveexec_b64 s[6:7], s[4:5]
	s_cbranch_execz .LBB0_1541
	ds_read_b128 v[94:97], v87
	ds_read_b128 v[98:101], v87 offset:2048
	ds_read_b128 v[102:105], v86
	ds_read_b128 v[106:109], v86 offset:2048
	s_waitcnt lgkmcnt(0)
	v_mfma_f32_16x16x32_bf16 v[34:37], v[94:97], v[102:105], v[34:37]
	v_mfma_f32_16x16x32_bf16 v[30:33], v[98:101], v[102:105], v[30:33]
	v_mfma_f32_16x16x32_bf16 v[26:29], v[94:97], v[106:109], v[26:29]
	v_mfma_f32_16x16x32_bf16 v[22:25], v[98:101], v[106:109], v[22:25]
	ds_read_b128 v[102:105], v86 offset:4096
	ds_read_b128 v[106:109], v86 offset:6144
	s_waitcnt lgkmcnt(0)
	v_mfma_f32_16x16x32_bf16 v[18:21], v[94:97], v[102:105], v[18:21]
	v_mfma_f32_16x16x32_bf16 v[10:13], v[94:97], v[106:109], v[10:13]
	ds_read_b128 v[94:97], v89
	v_mfma_f32_16x16x32_bf16 v[14:17], v[98:101], v[102:105], v[14:17]
	v_mfma_f32_16x16x32_bf16 v[4:7], v[98:101], v[106:109], v[6:9]
	ds_read_b128 v[98:101], v89 offset:2048
	ds_read_b128 v[102:105], v88
	ds_read_b128 v[106:109], v88 offset:2048
	s_waitcnt lgkmcnt(0)
	v_mfma_f32_16x16x32_bf16 v[34:37], v[94:97], v[102:105], v[34:37]
	v_mfma_f32_16x16x32_bf16 v[30:33], v[98:101], v[102:105], v[30:33]
	v_mfma_f32_16x16x32_bf16 v[26:29], v[94:97], v[106:109], v[26:29]
	v_mfma_f32_16x16x32_bf16 v[22:25], v[98:101], v[106:109], v[22:25]
	ds_read_b128 v[102:105], v88 offset:4096
	ds_read_b128 v[106:109], v88 offset:6144
	s_waitcnt lgkmcnt(0)
	v_mfma_f32_16x16x32_bf16 v[18:21], v[94:97], v[102:105], v[18:21]
	v_mfma_f32_16x16x32_bf16 v[14:17], v[98:101], v[102:105], v[14:17]
	v_mfma_f32_16x16x32_bf16 v[10:13], v[94:97], v[106:109], v[10:13]
	v_mfma_f32_16x16x32_bf16 v[6:9], v[98:101], v[106:109], v[4:7]
.LBB0_1541:
	s_or_b64 exec, exec, s[6:7]
	s_waitcnt vmcnt(4)
	s_barrier
	v_readfirstlane_b32 s6, v56
	s_add_i32 m0, s6, 0x10000
	v_lshl_add_u64 v[4:5], v[46:47], 0, s[50:51]
	global_load_lds_dwordx4 v[4:5], off
	s_cmp_ge_u32 s6, 0x1000
	s_cbranch_scc1 .Lthin_nb_10
	v_or_b32_e32 v2, 0x280, v38
	s_add_i32 m0, s6, 0x18000
	v_lshl_add_u64 v[4:5], v[2:3], 1, s[18:19]
	global_load_lds_dwordx4 v[4:5], off
.Lthin_nb_10:
	s_add_i32 m0, s6, 0x12000
	v_lshl_add_u64 v[4:5], v[48:49], 0, s[50:51]
	global_load_lds_dwordx4 v[4:5], off
	s_add_i32 m0, s6, 0x14000
	v_lshl_add_u64 v[4:5], v[50:51], 0, s[50:51]
	global_load_lds_dwordx4 v[4:5], off
	s_add_i32 m0, s6, 0x16000
	v_lshl_add_u64 v[4:5], v[52:53], 0, s[50:51]
	global_load_lds_dwordx4 v[4:5], off
	s_and_saveexec_b64 s[6:7], s[4:5]
	s_cbranch_execz .LBB0_1543
	ds_read_b128 v[94:97], v119 offset:32768
	ds_read_b128 v[98:101], v119 offset:34816
	ds_read_b128 v[102:105], v118
	ds_read_b128 v[106:109], v118 offset:2048
	s_waitcnt lgkmcnt(0)
	v_mfma_f32_16x16x32_bf16 v[34:37], v[94:97], v[102:105], v[34:37]
	v_mfma_f32_16x16x32_bf16 v[30:33], v[98:101], v[102:105], v[30:33]
	v_mfma_f32_16x16x32_bf16 v[26:29], v[94:97], v[106:109], v[26:29]
	v_mfma_f32_16x16x32_bf16 v[22:25], v[98:101], v[106:109], v[22:25]
	ds_read_b128 v[102:105], v118 offset:4096
	ds_read_b128 v[106:109], v118 offset:6144
	s_waitcnt lgkmcnt(0)
	v_mfma_f32_16x16x32_bf16 v[18:21], v[94:97], v[102:105], v[18:21]
	v_mfma_f32_16x16x32_bf16 v[10:13], v[94:97], v[106:109], v[10:13]
	ds_read_b128 v[94:97], v121 offset:32768
	v_mfma_f32_16x16x32_bf16 v[14:17], v[98:101], v[102:105], v[14:17]
	v_mfma_f32_16x16x32_bf16 v[4:7], v[98:101], v[106:109], v[6:9]
	ds_read_b128 v[98:101], v121 offset:34816
	ds_read_b128 v[102:105], v120
	ds_read_b128 v[106:109], v120 offset:2048
	s_waitcnt lgkmcnt(0)
	v_mfma_f32_16x16x32_bf16 v[34:37], v[94:97], v[102:105], v[34:37]
	v_mfma_f32_16x16x32_bf16 v[30:33], v[98:101], v[102:105], v[30:33]
	v_mfma_f32_16x16x32_bf16 v[26:29], v[94:97], v[106:109], v[26:29]
	v_mfma_f32_16x16x32_bf16 v[22:25], v[98:101], v[106:109], v[22:25]
	ds_read_b128 v[102:105], v120 offset:4096
	ds_read_b128 v[106:109], v120 offset:6144
	s_waitcnt lgkmcnt(0)
	v_mfma_f32_16x16x32_bf16 v[18:21], v[94:97], v[102:105], v[18:21]
	v_mfma_f32_16x16x32_bf16 v[14:17], v[98:101], v[102:105], v[14:17]
	v_mfma_f32_16x16x32_bf16 v[10:13], v[94:97], v[106:109], v[10:13]
	v_mfma_f32_16x16x32_bf16 v[6:9], v[98:101], v[106:109], v[4:7]
.LBB0_1543:
	s_or_b64 exec, exec, s[6:7]
	s_waitcnt vmcnt(4)
	s_barrier
	v_readfirstlane_b32 s6, v56
	s_add_i32 m0, s6, 0x1a000
	v_lshl_add_u64 v[4:5], v[46:47], 0, s[56:57]
	global_load_lds_dwordx4 v[4:5], off
	s_cmp_ge_u32 s6, 0x1000
	s_cbranch_scc1 .Lthin_nb_11
	v_or_b32_e32 v2, 0x2c0, v38
	s_add_i32 m0, s6, 0x22000
	v_lshl_add_u64 v[4:5], v[2:3], 1, s[18:19]
	global_load_lds_dwordx4 v[4:5], off
; #define GLDS16(gp, lp) __builtin_amdgcn_global_load_lds((const unsigned*)(gp), (__attribute__((address_space(3))) unsigned*)(lp), 16, 0, 0)
; template <bool SWAP, class Epi, bool THIN = false> ...
;     ...
;     for (int st = 0; st < ns; ++st) {
;       asm volatile("s_waitcnt vmcnt(0)" ::: "memory");
;       __builtin_amdgcn_s_barrier();
;       asm volatile("" ::: "memory");
;       if (st + 1 < ns) {
;         char* nb = smem + ((st + 1) & 1) * 65536;
;         const int ko = (st + 1) * 64;
; #pragma unroll
;         for (int i = 0; i < 4; ++i) { GLDS16(A + (size_t)(ap[i] + ko), nb + tid * 16 + i * 8192); GLDS16(Bt + (size_t)(bp[i] + ko), nb + 32768 + tid * 16 + i * 8192); }
;       }
;       const char* sa = smem + (st & 1) * 65536 + (wr * 64 + fr) * 128;
;       const char* sb = smem + (st & 1) * 65536 + 32768 + (wc * 128 + fr) * 128;
;       if constexpr (THIN) {
;         if (wc == 0) {
; #pragma unroll
;           for (int ks = 0; ks < 2; ++ks) {
;             bf16x8 af[4], bf[2];
; #pragma unroll
;             for (int m = 0; m < 4; ++m) af[m] = *(const bf16x8*)(sa + m * 2048 + (((ks * 4 + fq) ^ swz) << 4));
; #pragma unroll
;             for (int n = 0; n < 2; ++n) bf[n] = *(const bf16x8*)(sb + n * 2048 + (((ks * 4 + fq) ^ swz) << 4));
; #pragma unroll
;             for (int m = 0; m < 4; ++m)
; #pragma unroll
;               for (int n = 0; n < 2; ++n)
;                 acc[m][n] = SWAP ? __builtin_amdgcn_mfma_f32_16x16x32_bf16(bf[n], af[m], acc[m][n], 0, 0, 0)
;                                  : __builtin_amdgcn_mfma_f32_16x16x32_bf16(af[m], bf[n], acc[m][n], 0, 0, 0);
;           }
;         }
.Lthin_nb_11:
	s_add_i32 m0, s6, 0x1c000
	v_lshl_add_u64 v[4:5], v[48:49], 0, s[56:57]
	global_load_lds_dwordx4 v[4:5], off
	s_add_i32 m0, s6, 0x1e000
	v_lshl_add_u64 v[4:5], v[50:51], 0, s[56:57]
	global_load_lds_dwordx4 v[4:5], off
	s_add_i32 m0, s6, 0x20000
	v_lshl_add_u64 v[4:5], v[52:53], 0, s[56:57]
	global_load_lds_dwordx4 v[4:5], off
	s_and_saveexec_b64 s[6:7], s[4:5]
	s_cbranch_execz .LBB0_1545
	ds_read_b128 v[94:97], v83 offset:32768
	ds_read_b128 v[98:101], v83 offset:34816
	ds_read_b128 v[102:105], v82
	ds_read_b128 v[106:109], v82 offset:2048
	s_waitcnt lgkmcnt(0)
	v_mfma_f32_16x16x32_bf16 v[34:37], v[94:97], v[102:105], v[34:37]
	v_mfma_f32_16x16x32_bf16 v[30:33], v[98:101], v[102:105], v[30:33]
	v_mfma_f32_16x16x32_bf16 v[26:29], v[94:97], v[106:109], v[26:29]
	v_mfma_f32_16x16x32_bf16 v[22:25], v[98:101], v[106:109], v[22:25]
	ds_read_b128 v[102:105], v82 offset:4096
	ds_read_b128 v[106:109], v82 offset:6144
	s_waitcnt lgkmcnt(0)
	v_mfma_f32_16x16x32_bf16 v[18:21], v[94:97], v[102:105], v[18:21]
	v_mfma_f32_16x16x32_bf16 v[10:13], v[94:97], v[106:109], v[10:13]
	ds_read_b128 v[94:97], v85 offset:32768
	v_mfma_f32_16x16x32_bf16 v[14:17], v[98:101], v[102:105], v[14:17]
	v_mfma_f32_16x16x32_bf16 v[4:7], v[98:101], v[106:109], v[6:9]
	ds_read_b128 v[98:101], v85 offset:34816
	ds_read_b128 v[102:105], v84
	ds_read_b128 v[106:109], v84 offset:2048
	s_waitcnt lgkmcnt(0)
	v_mfma_f32_16x16x32_bf16 v[34:37], v[94:97], v[102:105], v[34:37]
	v_mfma_f32_16x16x32_bf16 v[30:33], v[98:101], v[102:105], v[30:33]
	v_mfma_f32_16x16x32_bf16 v[26:29], v[94:97], v[106:109], v[26:29]
	v_mfma_f32_16x16x32_bf16 v[22:25], v[98:101], v[106:109], v[22:25]
	ds_read_b128 v[102:105], v84 offset:4096
	ds_read_b128 v[106:109], v84 offset:6144
	s_waitcnt lgkmcnt(0)
	v_mfma_f32_16x16x32_bf16 v[18:21], v[94:97], v[102:105], v[18:21]
	v_mfma_f32_16x16x32_bf16 v[14:17], v[98:101], v[102:105], v[14:17]
	v_mfma_f32_16x16x32_bf16 v[10:13], v[94:97], v[106:109], v[10:13]
	v_mfma_f32_16x16x32_bf16 v[6:9], v[98:101], v[106:109], v[4:7]
.LBB0_1545:
	s_or_b64 exec, exec, s[6:7]
	s_waitcnt vmcnt(4)
	s_barrier
	v_readfirstlane_b32 s6, v56
	s_add_i32 m0, s6, 0x0
	v_lshl_add_u64 v[4:5], v[46:47], 0, s[58:59]
	global_load_lds_dwordx4 v[4:5], off
	s_cmp_ge_u32 s6, 0x1000
	s_cbranch_scc1 .Lthin_nb_12
	v_or_b32_e32 v2, 0x300, v38
	s_add_i32 m0, s6, 0x8000
	v_lshl_add_u64 v[4:5], v[2:3], 1, s[18:19]
	global_load_lds_dwordx4 v[4:5], off
.Lthin_nb_12:
	s_add_i32 m0, s6, 0x2000
	v_lshl_add_u64 v[4:5], v[48:49], 0, s[58:59]
	global_load_lds_dwordx4 v[4:5], off
	s_add_i32 m0, s6, 0x4000
	v_lshl_add_u64 v[4:5], v[50:51], 0, s[58:59]
	global_load_lds_dwordx4 v[4:5], off
	s_add_i32 m0, s6, 0x6000
	v_lshl_add_u64 v[4:5], v[52:53], 0, s[58:59]
	global_load_lds_dwordx4 v[4:5], off
	s_and_saveexec_b64 s[6:7], s[4:5]
	s_cbranch_execz .LBB0_1547
	ds_read_b128 v[94:97], v87
	ds_read_b128 v[98:101], v87 offset:2048
	ds_read_b128 v[102:105], v86
	ds_read_b128 v[106:109], v86 offset:2048
	s_waitcnt lgkmcnt(0)
	v_mfma_f32_16x16x32_bf16 v[34:37], v[94:97], v[102:105], v[34:37]
	v_mfma_f32_16x16x32_bf16 v[30:33], v[98:101], v[102:105], v[30:33]
	v_mfma_f32_16x16x32_bf16 v[26:29], v[94:97], v[106:109], v[26:29]
	v_mfma_f32_16x16x32_bf16 v[22:25], v[98:101], v[106:109], v[22:25]
	ds_read_b128 v[102:105], v86 offset:4096
	ds_read_b128 v[106:109], v86 offset:6144
	s_waitcnt lgkmcnt(0)
	v_mfma_f32_16x16x32_bf16 v[18:21], v[94:97], v[102:105], v[18:21]
	v_mfma_f32_16x16x32_bf16 v[10:13], v[94:97], v[106:109], v[10:13]
	ds_read_b128 v[94:97], v89
	v_mfma_f32_16x16x32_bf16 v[14:17], v[98:101], v[102:105], v[14:17]
	v_mfma_f32_16x16x32_bf16 v[4:7], v[98:101], v[106:109], v[6:9]
	ds_read_b128 v[98:101], v89 offset:2048
	ds_read_b128 v[102:105], v88
	ds_read_b128 v[106:109], v88 offset:2048
	s_waitcnt lgkmcnt(0)
	v_mfma_f32_16x16x32_bf16 v[34:37], v[94:97], v[102:105], v[34:37]
	v_mfma_f32_16x16x32_bf16 v[30:33], v[98:101], v[102:105], v[30:33]
	v_mfma_f32_16x16x32_bf16 v[26:29], v[94:97], v[106:109], v[26:29]
	v_mfma_f32_16x16x32_bf16 v[22:25], v[98:101], v[106:109], v[22:25]
	ds_read_b128 v[102:105], v88 offset:4096
	ds_read_b128 v[106:109], v88 offset:6144
	s_waitcnt lgkmcnt(0)
	v_mfma_f32_16x16x32_bf16 v[18:21], v[94:97], v[102:105], v[18:21]
	v_mfma_f32_16x16x32_bf16 v[14:17], v[98:101], v[102:105], v[14:17]
	v_mfma_f32_16x16x32_bf16 v[10:13], v[94:97], v[106:109], v[10:13]
	v_mfma_f32_16x16x32_bf16 v[6:9], v[98:101], v[106:109], v[4:7]
.LBB0_1547:
	s_or_b64 exec, exec, s[6:7]
	s_waitcnt vmcnt(4)
	s_barrier
	v_readfirstlane_b32 s6, v56
	s_add_i32 m0, s6, 0x10000
	v_lshl_add_u64 v[4:5], v[46:47], 0, s[60:61]
	global_load_lds_dwordx4 v[4:5], off
	s_cmp_ge_u32 s6, 0x1000
	s_cbranch_scc1 .Lthin_nb_13
	v_or_b32_e32 v2, 0x340, v38
	s_add_i32 m0, s6, 0x18000
	v_lshl_add_u64 v[4:5], v[2:3], 1, s[18:19]
	global_load_lds_dwordx4 v[4:5], off
; #define GLDS16(gp, lp) __builtin_amdgcn_global_load_lds((const unsigned*)(gp), (__attribute__((address_space(3))) unsigned*)(lp), 16, 0, 0)
; template <bool SWAP, class Epi, bool THIN = false> ...
;     ...
;     for (int st = 0; st < ns; ++st) {
;       asm volatile("s_waitcnt vmcnt(0)" ::: "memory");
;       __builtin_amdgcn_s_barrier();
;       asm volatile("" ::: "memory");
;       if (st + 1 < ns) {
;         char* nb = smem + ((st + 1) & 1) * 65536;
;         const int ko = (st + 1) * 64;
; #pragma unroll
;         for (int i = 0; i < 4; ++i) { GLDS16(A + (size_t)(ap[i] + ko), nb + tid * 16 + i * 8192); GLDS16(Bt + (size_t)(bp[i] + ko), nb + 32768 + tid * 16 + i * 8192); }
;       }
;       const char* sa = smem + (st & 1) * 65536 + (wr * 64 + fr) * 128;
;       const char* sb = smem + (st & 1) * 65536 + 32768 + (wc * 128 + fr) * 128;
;       if constexpr (THIN) {
;         if (wc == 0) {
; #pragma unroll
;           for (int ks = 0; ks < 2; ++ks) {
;             bf16x8 af[4], bf[2];
; #pragma unroll
;             for (int m = 0; m < 4; ++m) af[m] = *(const bf16x8*)(sa + m * 2048 + (((ks * 4 + fq) ^ swz) << 4));
; #pragma unroll
;             for (int n = 0; n < 2; ++n) bf[n] = *(const bf16x8*)(sb + n * 2048 + (((ks * 4 + fq) ^ swz) << 4));
; #pragma unroll
;             for (int m = 0; m < 4; ++m)
; #pragma unroll
;               for (int n = 0; n < 2; ++n)
;                 acc[m][n] = SWAP ? __builtin_amdgcn_mfma_f32_16x16x32_bf16(bf[n], af[m], acc[m][n], 0, 0, 0)
;                                  : __builtin_amdgcn_mfma_f32_16x16x32_bf16(af[m], bf[n], acc[m][n], 0, 0, 0);
;           }
;         }
.Lthin_nb_13:
	s_add_i32 m0, s6, 0x12000
	v_lshl_add_u64 v[4:5], v[48:49], 0, s[60:61]
	global_load_lds_dwordx4 v[4:5], off
	s_add_i32 m0, s6, 0x14000
	v_lshl_add_u64 v[4:5], v[50:51], 0, s[60:61]
	global_load_lds_dwordx4 v[4:5], off
	s_add_i32 m0, s6, 0x16000
	v_lshl_add_u64 v[4:5], v[52:53], 0, s[60:61]
	global_load_lds_dwordx4 v[4:5], off
	s_and_saveexec_b64 s[6:7], s[4:5]
	s_cbranch_execz .LBB0_1549
	ds_read_b128 v[94:97], v119 offset:32768
	ds_read_b128 v[98:101], v119 offset:34816
	ds_read_b128 v[102:105], v118
	ds_read_b128 v[106:109], v118 offset:2048
	s_waitcnt lgkmcnt(0)
	v_mfma_f32_16x16x32_bf16 v[34:37], v[94:97], v[102:105], v[34:37]
	v_mfma_f32_16x16x32_bf16 v[30:33], v[98:101], v[102:105], v[30:33]
	v_mfma_f32_16x16x32_bf16 v[26:29], v[94:97], v[106:109], v[26:29]
	v_mfma_f32_16x16x32_bf16 v[22:25], v[98:101], v[106:109], v[22:25]
	ds_read_b128 v[102:105], v118 offset:4096
	ds_read_b128 v[106:109], v118 offset:6144
	s_waitcnt lgkmcnt(0)
	v_mfma_f32_16x16x32_bf16 v[18:21], v[94:97], v[102:105], v[18:21]
	v_mfma_f32_16x16x32_bf16 v[10:13], v[94:97], v[106:109], v[10:13]
	ds_read_b128 v[94:97], v121 offset:32768
	v_mfma_f32_16x16x32_bf16 v[14:17], v[98:101], v[102:105], v[14:17]
	v_mfma_f32_16x16x32_bf16 v[4:7], v[98:101], v[106:109], v[6:9]
	ds_read_b128 v[98:101], v121 offset:34816
	ds_read_b128 v[102:105], v120
	ds_read_b128 v[106:109], v120 offset:2048
	s_waitcnt lgkmcnt(0)
	v_mfma_f32_16x16x32_bf16 v[34:37], v[94:97], v[102:105], v[34:37]
	v_mfma_f32_16x16x32_bf16 v[30:33], v[98:101], v[102:105], v[30:33]
	v_mfma_f32_16x16x32_bf16 v[26:29], v[94:97], v[106:109], v[26:29]
	v_mfma_f32_16x16x32_bf16 v[22:25], v[98:101], v[106:109], v[22:25]
	ds_read_b128 v[102:105], v120 offset:4096
	ds_read_b128 v[106:109], v120 offset:6144
	s_waitcnt lgkmcnt(0)
	v_mfma_f32_16x16x32_bf16 v[18:21], v[94:97], v[102:105], v[18:21]
	v_mfma_f32_16x16x32_bf16 v[14:17], v[98:101], v[102:105], v[14:17]
	v_mfma_f32_16x16x32_bf16 v[10:13], v[94:97], v[106:109], v[10:13]
	v_mfma_f32_16x16x32_bf16 v[6:9], v[98:101], v[106:109], v[4:7]
.LBB0_1549:
	s_or_b64 exec, exec, s[6:7]
	s_waitcnt vmcnt(4)
	s_barrier
	v_readfirstlane_b32 s6, v56
	s_add_i32 m0, s6, 0x1a000
	v_lshl_add_u64 v[4:5], v[46:47], 0, s[62:63]
	global_load_lds_dwordx4 v[4:5], off
	s_cmp_ge_u32 s6, 0x1000
	s_cbranch_scc1 .Lthin_nb_14
	v_or_b32_e32 v2, 0x380, v38
	s_add_i32 m0, s6, 0x22000
	v_lshl_add_u64 v[4:5], v[2:3], 1, s[18:19]
	global_load_lds_dwordx4 v[4:5], off
.Lthin_nb_14:
	s_add_i32 m0, s6, 0x1c000
	v_lshl_add_u64 v[4:5], v[48:49], 0, s[62:63]
	global_load_lds_dwordx4 v[4:5], off
	s_add_i32 m0, s6, 0x1e000
	v_lshl_add_u64 v[4:5], v[50:51], 0, s[62:63]
	global_load_lds_dwordx4 v[4:5], off
	s_add_i32 m0, s6, 0x20000
	v_lshl_add_u64 v[4:5], v[52:53], 0, s[62:63]
	global_load_lds_dwordx4 v[4:5], off
	s_and_saveexec_b64 s[6:7], s[4:5]
	s_cbranch_execz .LBB0_1551
	ds_read_b128 v[94:97], v83 offset:32768
	ds_read_b128 v[98:101], v83 offset:34816
	ds_read_b128 v[102:105], v82
	ds_read_b128 v[106:109], v82 offset:2048
	s_waitcnt lgkmcnt(0)
	v_mfma_f32_16x16x32_bf16 v[34:37], v[94:97], v[102:105], v[34:37]
	v_mfma_f32_16x16x32_bf16 v[30:33], v[98:101], v[102:105], v[30:33]
	v_mfma_f32_16x16x32_bf16 v[26:29], v[94:97], v[106:109], v[26:29]
	v_mfma_f32_16x16x32_bf16 v[22:25], v[98:101], v[106:109], v[22:25]
	ds_read_b128 v[102:105], v82 offset:4096
	ds_read_b128 v[106:109], v82 offset:6144
	s_waitcnt lgkmcnt(0)
	v_mfma_f32_16x16x32_bf16 v[18:21], v[94:97], v[102:105], v[18:21]
	v_mfma_f32_16x16x32_bf16 v[10:13], v[94:97], v[106:109], v[10:13]
	ds_read_b128 v[94:97], v85 offset:32768
	v_mfma_f32_16x16x32_bf16 v[14:17], v[98:101], v[102:105], v[14:17]
	v_mfma_f32_16x16x32_bf16 v[4:7], v[98:101], v[106:109], v[6:9]
	ds_read_b128 v[98:101], v85 offset:34816
	ds_read_b128 v[102:105], v84
	ds_read_b128 v[106:109], v84 offset:2048
	s_waitcnt lgkmcnt(0)
	v_mfma_f32_16x16x32_bf16 v[34:37], v[94:97], v[102:105], v[34:37]
	v_mfma_f32_16x16x32_bf16 v[30:33], v[98:101], v[102:105], v[30:33]
	v_mfma_f32_16x16x32_bf16 v[26:29], v[94:97], v[106:109], v[26:29]
	v_mfma_f32_16x16x32_bf16 v[22:25], v[98:101], v[106:109], v[22:25]
	ds_read_b128 v[102:105], v84 offset:4096
	ds_read_b128 v[106:109], v84 offset:6144
	s_waitcnt lgkmcnt(0)
	v_mfma_f32_16x16x32_bf16 v[18:21], v[94:97], v[102:105], v[18:21]
	v_mfma_f32_16x16x32_bf16 v[14:17], v[98:101], v[102:105], v[14:17]
	v_mfma_f32_16x16x32_bf16 v[10:13], v[94:97], v[106:109], v[10:13]
	v_mfma_f32_16x16x32_bf16 v[6:9], v[98:101], v[106:109], v[4:7]
; #define GLDS16(gp, lp) __builtin_amdgcn_global_load_lds((const unsigned*)(gp), (__attribute__((address_space(3))) unsigned*)(lp), 16, 0, 0)
; template <bool SWAP, class Epi, bool THIN = false> ...
;     ...
;     for (int st = 0; st < ns; ++st) {
;       asm volatile("s_waitcnt vmcnt(0)" ::: "memory");
;       __builtin_amdgcn_s_barrier();
;       asm volatile("" ::: "memory");
;       if (st + 1 < ns) {
;         char* nb = smem + ((st + 1) & 1) * 65536;
;         const int ko = (st + 1) * 64;
; #pragma unroll
;         for (int i = 0; i < 4; ++i) { GLDS16(A + (size_t)(ap[i] + ko), nb + tid * 16 + i * 8192); GLDS16(Bt + (size_t)(bp[i] + ko), nb + 32768 + tid * 16 + i * 8192); }
;       }
;       const char* sa = smem + (st & 1) * 65536 + (wr * 64 + fr) * 128;
;       const char* sb = smem + (st & 1) * 65536 + 32768 + (wc * 128 + fr) * 128;
;       if constexpr (THIN) {
;         if (wc == 0) {
; #pragma unroll
;           for (int ks = 0; ks < 2; ++ks) {
;             bf16x8 af[4], bf[2];
; #pragma unroll
;             for (int m = 0; m < 4; ++m) af[m] = *(const bf16x8*)(sa + m * 2048 + (((ks * 4 + fq) ^ swz) << 4));
; #pragma unroll
;             for (int n = 0; n < 2; ++n) bf[n] = *(const bf16x8*)(sb + n * 2048 + (((ks * 4 + fq) ^ swz) << 4));
; #pragma unroll
;             for (int m = 0; m < 4; ++m)
; #pragma unroll
;               for (int n = 0; n < 2; ++n)
;                 acc[m][n] = SWAP ? __builtin_amdgcn_mfma_f32_16x16x32_bf16(bf[n], af[m], acc[m][n], 0, 0, 0)
;                                  : __builtin_amdgcn_mfma_f32_16x16x32_bf16(af[m], bf[n], acc[m][n], 0, 0, 0);
;           }
;         }
.LBB0_1551:
	s_or_b64 exec, exec, s[6:7]
	s_waitcnt vmcnt(4)
	s_barrier
	v_readfirstlane_b32 s6, v56
	s_add_i32 m0, s6, 0x0
	v_lshl_add_u64 v[4:5], v[46:47], 0, s[64:65]
	global_load_lds_dwordx4 v[4:5], off
	s_cmp_ge_u32 s6, 0x1000
	s_cbranch_scc1 .Lthin_nb_15
	v_or_b32_e32 v2, 0x3c0, v38
	s_add_i32 m0, s6, 0x8000
	v_lshl_add_u64 v[4:5], v[2:3], 1, s[18:19]
	global_load_lds_dwordx4 v[4:5], off
.Lthin_nb_15:
	s_add_i32 m0, s6, 0x2000
	v_lshl_add_u64 v[4:5], v[48:49], 0, s[64:65]
	global_load_lds_dwordx4 v[4:5], off
	s_add_i32 m0, s6, 0x4000
	v_lshl_add_u64 v[4:5], v[50:51], 0, s[64:65]
	global_load_lds_dwordx4 v[4:5], off
	s_add_i32 m0, s6, 0x6000
	v_lshl_add_u64 v[4:5], v[52:53], 0, s[64:65]
	global_load_lds_dwordx4 v[4:5], off
	s_and_saveexec_b64 s[6:7], s[4:5]
	s_cbranch_execz .LBB0_1553
	ds_read_b128 v[94:97], v87
	ds_read_b128 v[98:101], v87 offset:2048
	ds_read_b128 v[102:105], v86
	ds_read_b128 v[106:109], v86 offset:2048
	s_waitcnt lgkmcnt(0)
	v_mfma_f32_16x16x32_bf16 v[34:37], v[94:97], v[102:105], v[34:37]
	v_mfma_f32_16x16x32_bf16 v[30:33], v[98:101], v[102:105], v[30:33]
	v_mfma_f32_16x16x32_bf16 v[26:29], v[94:97], v[106:109], v[26:29]
	v_mfma_f32_16x16x32_bf16 v[22:25], v[98:101], v[106:109], v[22:25]
	ds_read_b128 v[102:105], v86 offset:4096
	ds_read_b128 v[106:109], v86 offset:6144
	s_waitcnt lgkmcnt(0)
	v_mfma_f32_16x16x32_bf16 v[18:21], v[94:97], v[102:105], v[18:21]
	v_mfma_f32_16x16x32_bf16 v[10:13], v[94:97], v[106:109], v[10:13]
	ds_read_b128 v[94:97], v89
	v_mfma_f32_16x16x32_bf16 v[14:17], v[98:101], v[102:105], v[14:17]
	v_mfma_f32_16x16x32_bf16 v[4:7], v[98:101], v[106:109], v[6:9]
	ds_read_b128 v[98:101], v89 offset:2048
	ds_read_b128 v[102:105], v88
	ds_read_b128 v[106:109], v88 offset:2048
	s_waitcnt lgkmcnt(0)
	v_mfma_f32_16x16x32_bf16 v[34:37], v[94:97], v[102:105], v[34:37]
	v_mfma_f32_16x16x32_bf16 v[30:33], v[98:101], v[102:105], v[30:33]
	v_mfma_f32_16x16x32_bf16 v[26:29], v[94:97], v[106:109], v[26:29]
	v_mfma_f32_16x16x32_bf16 v[22:25], v[98:101], v[106:109], v[22:25]
	ds_read_b128 v[102:105], v88 offset:4096
	ds_read_b128 v[106:109], v88 offset:6144
	s_waitcnt lgkmcnt(0)
	v_mfma_f32_16x16x32_bf16 v[18:21], v[94:97], v[102:105], v[18:21]
	v_mfma_f32_16x16x32_bf16 v[14:17], v[98:101], v[102:105], v[14:17]
	v_mfma_f32_16x16x32_bf16 v[10:13], v[94:97], v[106:109], v[10:13]
	v_mfma_f32_16x16x32_bf16 v[6:9], v[98:101], v[106:109], v[4:7]
.LBB0_1553:
	s_or_b64 exec, exec, s[6:7]
	s_waitcnt vmcnt(4)
	s_barrier
	s_and_saveexec_b64 s[6:7], s[4:5]
	s_cbranch_execz .LBB0_1555
	ds_read_b128 v[38:41], v119 offset:32768
	ds_read_b128 v[42:45], v119 offset:34816
	ds_read_b128 v[46:49], v118
	ds_read_b128 v[50:53], v118 offset:2048
	s_waitcnt lgkmcnt(0)
	v_mfma_f32_16x16x32_bf16 v[34:37], v[38:41], v[46:49], v[34:37]
	v_mfma_f32_16x16x32_bf16 v[30:33], v[42:45], v[46:49], v[30:33]
	v_mfma_f32_16x16x32_bf16 v[26:29], v[38:41], v[50:53], v[26:29]
	v_mfma_f32_16x16x32_bf16 v[22:25], v[42:45], v[50:53], v[22:25]
	ds_read_b128 v[46:49], v118 offset:4096
	ds_read_b128 v[50:53], v118 offset:6144
	s_waitcnt lgkmcnt(0)
	v_mfma_f32_16x16x32_bf16 v[18:21], v[38:41], v[46:49], v[18:21]
	v_mfma_f32_16x16x32_bf16 v[10:13], v[38:41], v[50:53], v[10:13]
	ds_read_b128 v[38:41], v121 offset:32768
	v_mfma_f32_16x16x32_bf16 v[14:17], v[42:45], v[46:49], v[14:17]
	v_mfma_f32_16x16x32_bf16 v[4:7], v[42:45], v[50:53], v[6:9]
	ds_read_b128 v[42:45], v121 offset:34816
	ds_read_b128 v[46:49], v120
	ds_read_b128 v[50:53], v120 offset:2048
	s_waitcnt lgkmcnt(0)
	v_mfma_f32_16x16x32_bf16 v[34:37], v[38:41], v[46:49], v[34:37]
	v_mfma_f32_16x16x32_bf16 v[30:33], v[42:45], v[46:49], v[30:33]
	v_mfma_f32_16x16x32_bf16 v[26:29], v[38:41], v[50:53], v[26:29]
	v_mfma_f32_16x16x32_bf16 v[22:25], v[42:45], v[50:53], v[22:25]
	ds_read_b128 v[46:49], v120 offset:4096
	ds_read_b128 v[50:53], v120 offset:6144
	s_waitcnt lgkmcnt(0)
	v_mfma_f32_16x16x32_bf16 v[18:21], v[38:41], v[46:49], v[18:21]
	v_mfma_f32_16x16x32_bf16 v[14:17], v[42:45], v[46:49], v[14:17]
	v_mfma_f32_16x16x32_bf16 v[10:13], v[38:41], v[50:53], v[10:13]
	v_mfma_f32_16x16x32_bf16 v[6:9], v[42:45], v[50:53], v[4:7]
